# P16 residual epilogue: bf16 residual fetched three groups ahead through a 4-slot register ring, counted waits (on v67)
# speedup vs baseline: 1.0015x; 1.0015x over previous
; __device__ __forceinline__ unsigned pk2(float lo, float hi) { f32x2 v = {lo, hi}; bf16x2_t b = __builtin_convertvector(v, bf16x2_t); return __builtin_bit_cast(unsigned, b); }
;     __device__ __forceinline__ void operator()(const f32x4 (&acc)[2][2][4][2], const Unit& u, int wr, int wc, int fr, int fq) const {
;         const int row0 = u.pm * BM + wr * 64 + fr; const int b = (u.pm * BM) / S;
;         f32x4 gv[2][2];
; #pragma unroll
;         for (int bj = 0; bj < 2; ++bj)
; #pragma unroll
;             for (int n = 0; n < 2; ++n) gv[bj][n] = *(const f32x4*)(gate + (size_t)b * 6144 + u.pn * BM + bj * HALF + wc * 32 + 8 * fq + 4 * n);
; #pragma unroll
;         for (int ai = 0; ai < 2; ++ai)
; #pragma unroll
;             for (int m = 0; m < 4; ++m) { const size_t off = (size_t)(row0 + ai * HALF + m * 16) * D + u.pn * BM + wc * 32 + 8 * fq;
; #pragma unroll
;                 for (int bj = 0; bj < 2; ++bj) { const size_t o = off + bj * HALF; f32x4 b0, b1;
;                     if (BASE_BF16) { const u32x4 r = *(const u32x4*)((const bf16_t*)base + o);
;                         b0 = (f32x4){__uint_as_float(r.x << 16), __uint_as_float(r.x & 0xffff0000u), __uint_as_float(r.y << 16), __uint_as_float(r.y & 0xffff0000u)};
;                         b1 = (f32x4){__uint_as_float(r.z << 16), __uint_as_float(r.z & 0xffff0000u), __uint_as_float(r.w << 16), __uint_as_float(r.w & 0xffff0000u)}; }
;                     else { b0 = *(const f32x4*)((const float*)base + o); b1 = *(const f32x4*)((const float*)base + o + 4); }
;                     const f32x4 v0 = b0 + gv[bj][0] * acc[ai][bj][m][0], v1 = b1 + gv[bj][1] * acc[ai][bj][m][1];
;                     u32x4 w; w.x = pk2(v0[0], v0[1]); w.y = pk2(v0[2], v0[3]); w.z = pk2(v1[0], v1[1]); w.w = pk2(v1[2], v1[3]);
;                     *(u32x4*)(out + o) = w; } }
.LBB0_1700:
	s_lshl_b32 s26, s59, 8
	s_add_i32 s30, s26, s43
	s_ashr_i32 s26, s59, 31
	s_lshr_b32 s26, s26, 29
	s_add_i32 s26, s59, s26
	s_ashr_i32 s26, s26, 3
	s_mul_hi_i32 s27, s26, 0x6000
	s_mulk_i32 s26, 0x6000
	s_add_u32 s31, s40, s26
	s_addc_u32 s34, s41, s27
	s_lshl_b32 s26, s60, 8
	s_ashr_i32 s27, s26, 31
	s_lshl_b64 s[28:29], s[26:27], 2
	s_add_u32 s28, s31, s28
	v_mbcnt_lo_u32_b32 v122, -1, 0
	v_mbcnt_hi_u32_b32 v122, -1, v122
	s_addc_u32 s29, s34, s29
	v_ashrrev_i32_e32 v120, 1, v122
	s_add_u32 s28, s28, s56
	v_and_b32_e32 v120, -8, v120
	v_and_or_b32 v164, v122, 15, s30
	s_addc_u32 s29, s29, 0
	v_ashrrev_i32_e32 v121, 31, v120
	s_or_b64 s[26:27], s[26:27], s[8:9]
	v_ashrrev_i32_e32 v165, 31, v164
	v_lshl_add_u64 v[162:163], s[26:27], 0, v[120:121]
	v_lshlrev_b64 v[122:123], 10, v[164:165]
	v_lshl_add_u64 v[122:123], v[162:163], 0, v[122:123]
	v_lshlrev_b64 v[160:161], 1, v[122:123]
	v_lshl_add_u64 v[174:175], s[44:45], 0, v[160:161]
	v_lshl_add_u64 v[124:125], v[120:121], 2, s[28:29]
	global_load_dwordx4 v[132:135], v[124:125], off
	global_load_dwordx4 v[128:131], v[124:125], off offset:16
	global_load_dwordx4 v[120:123], v[124:125], off offset:528
	s_nop 0
	global_load_dwordx4 v[124:127], v[124:125], off offset:512
	v_readlane_b32 s26, v254, 2
	v_readlane_b32 s27, v254, 3
	s_and_b64 vcc, exec, s[4:5]
	s_mov_b64 s[4:5], -1
	v_lshl_add_u64 v[176:177], s[26:27], 0, v[160:161]
	global_load_dwordx4 v[214:217], v[174:175], off
	global_load_dwordx4 v[218:221], v[174:175], off offset:256
	s_mov_b64 s[98:99], 0x8000
	v_lshl_add_u64 v[246:247], v[174:175], 0, s[98:99]
	global_load_dwordx4 v[222:225], v[246:247], off
	s_waitcnt vmcnt(2)
	v_lshlrev_b32_e32 v178, 16, v214
	v_and_b32_e32 v179, 0xffff0000, v214
	v_lshlrev_b32_e32 v170, 16, v215
	v_and_b32_e32 v171, 0xffff0000, v215
	v_lshlrev_b32_e32 v180, 16, v216
	v_and_b32_e32 v181, 0xffff0000, v216
	v_lshlrev_b32_e32 v172, 16, v217
	v_and_b32_e32 v173, 0xffff0000, v217
	v_pk_fma_f32 v[142:143], v[142:143], v[134:135], v[170:171]
	v_pk_fma_f32 v[140:141], v[140:141], v[132:133], v[178:179]
	v_pk_fma_f32 v[170:171], v[138:139], v[130:131], v[172:173]
	v_pk_fma_f32 v[138:139], v[136:137], v[128:129], v[180:181]
	v_cvt_pk_bf16_f32 v136, v140, v141
	v_cvt_pk_bf16_f32 v137, v142, v143
	v_cvt_pk_bf16_f32 v138, v138, v139
	v_cvt_pk_bf16_f32 v139, v170, v171
	global_store_dwordx4 v[176:177], v[136:139], off
	s_mov_b64 s[98:99], 0x8000
	v_lshl_add_u64 v[246:247], v[174:175], 0, s[98:99]
	global_load_dwordx4 v[226:229], v[246:247], off offset:256
	v_or_b32_e32 v140, 16, v164
	v_ashrrev_i32_e32 v141, 31, v140
	v_lshlrev_b64 v[140:141], 10, v[140:141]
	v_lshl_add_u64 v[140:141], v[140:141], 0, v[162:163]
	v_lshlrev_b64 v[140:141], 1, v[140:141]
	v_lshl_add_u64 v[142:143], s[44:45], 0, v[140:141]
	s_waitcnt vmcnt(3)
	v_lshlrev_b32_e32 v170, 16, v218
	v_and_b32_e32 v171, 0xffff0000, v218
	v_lshlrev_b32_e32 v136, 16, v219
	v_and_b32_e32 v137, 0xffff0000, v219
	v_lshlrev_b32_e32 v172, 16, v220
	v_and_b32_e32 v173, 0xffff0000, v220
	v_lshlrev_b32_e32 v138, 16, v221
	v_and_b32_e32 v139, 0xffff0000, v221
	v_pk_fma_f32 v[118:119], v[118:119], v[126:127], v[136:137]
	v_pk_fma_f32 v[116:117], v[116:117], v[124:125], v[170:171]
	v_pk_fma_f32 v[136:137], v[114:115], v[122:123], v[138:139]
	v_pk_fma_f32 v[114:115], v[112:113], v[120:121], v[172:173]
	v_cvt_pk_bf16_f32 v112, v116, v117
	v_cvt_pk_bf16_f32 v113, v118, v119
	v_cvt_pk_bf16_f32 v114, v114, v115
	v_cvt_pk_bf16_f32 v115, v136, v137
	global_store_dwordx4 v[176:177], v[112:115], off offset:256
	s_mov_b64 s[98:99], 0x10000
	v_lshl_add_u64 v[246:247], v[174:175], 0, s[98:99]
	global_load_dwordx4 v[214:217], v[246:247], off
	v_lshl_add_u64 v[116:117], s[26:27], 0, v[140:141]
	s_waitcnt vmcnt(4)
	v_lshlrev_b32_e32 v118, 16, v222
	v_and_b32_e32 v119, 0xffff0000, v222
	v_lshlrev_b32_e32 v112, 16, v223
	v_and_b32_e32 v113, 0xffff0000, v223
	v_lshlrev_b32_e32 v136, 16, v224
	v_and_b32_e32 v137, 0xffff0000, v224
	v_lshlrev_b32_e32 v114, 16, v225
	v_and_b32_e32 v115, 0xffff0000, v225
	v_pk_fma_f32 v[110:111], v[110:111], v[134:135], v[112:113]
	v_pk_fma_f32 v[108:109], v[108:109], v[132:133], v[118:119]
	v_pk_fma_f32 v[112:113], v[106:107], v[130:131], v[114:115]
	v_pk_fma_f32 v[106:107], v[104:105], v[128:129], v[136:137]
	v_cvt_pk_bf16_f32 v104, v108, v109
	v_cvt_pk_bf16_f32 v105, v110, v111
	v_cvt_pk_bf16_f32 v106, v106, v107
	v_cvt_pk_bf16_f32 v107, v112, v113
	global_store_dwordx4 v[116:117], v[104:107], off
	s_mov_b64 s[98:99], 0x10000
	v_lshl_add_u64 v[246:247], v[174:175], 0, s[98:99]
	global_load_dwordx4 v[218:221], v[246:247], off offset:256
	v_or_b32_e32 v108, 32, v164
	v_ashrrev_i32_e32 v109, 31, v108
	v_lshlrev_b64 v[108:109], 10, v[108:109]
	v_lshl_add_u64 v[108:109], v[108:109], 0, v[162:163]
	v_lshlrev_b64 v[108:109], 1, v[108:109]
	v_lshl_add_u64 v[110:111], s[44:45], 0, v[108:109]
	s_waitcnt vmcnt(4)
	v_lshlrev_b32_e32 v112, 16, v226
	v_and_b32_e32 v113, 0xffff0000, v226
	v_lshlrev_b32_e32 v104, 16, v227
	v_and_b32_e32 v105, 0xffff0000, v227
	v_lshlrev_b32_e32 v114, 16, v228
	v_and_b32_e32 v115, 0xffff0000, v228
	v_lshlrev_b32_e32 v106, 16, v229
	v_and_b32_e32 v107, 0xffff0000, v229
	v_pk_fma_f32 v[102:103], v[102:103], v[126:127], v[104:105]
	v_pk_fma_f32 v[100:101], v[100:101], v[124:125], v[112:113]
	v_pk_fma_f32 v[104:105], v[98:99], v[122:123], v[106:107]
	v_pk_fma_f32 v[98:99], v[96:97], v[120:121], v[114:115]
	v_cvt_pk_bf16_f32 v96, v100, v101
	v_cvt_pk_bf16_f32 v97, v102, v103
	v_cvt_pk_bf16_f32 v98, v98, v99
	v_cvt_pk_bf16_f32 v99, v104, v105
	global_store_dwordx4 v[116:117], v[96:99], off offset:256
	s_mov_b64 s[98:99], 0x18000
	v_lshl_add_u64 v[246:247], v[174:175], 0, s[98:99]
	global_load_dwordx4 v[222:225], v[246:247], off
	v_lshl_add_u64 v[100:101], s[26:27], 0, v[108:109]
	s_waitcnt vmcnt(4)
; __device__ __forceinline__ unsigned pk2(float lo, float hi) { f32x2 v = {lo, hi}; bf16x2_t b = __builtin_convertvector(v, bf16x2_t); return __builtin_bit_cast(unsigned, b); }
;     __device__ __forceinline__ void operator()(const f32x4 (&acc)[2][2][4][2], const Unit& u, int wr, int wc, int fr, int fq) const {
;     ...
;             for (int m = 0; m < 4; ++m) { const size_t off = (size_t)(row0 + ai * HALF + m * 16) * D + u.pn * BM + wc * 32 + 8 * fq;
; #pragma unroll
;                 for (int bj = 0; bj < 2; ++bj) { const size_t o = off + bj * HALF; f32x4 b0, b1;
;                     if (BASE_BF16) { const u32x4 r = *(const u32x4*)((const bf16_t*)base + o);
;                         b0 = (f32x4){__uint_as_float(r.x << 16), __uint_as_float(r.x & 0xffff0000u), __uint_as_float(r.y << 16), __uint_as_float(r.y & 0xffff0000u)};
;                         b1 = (f32x4){__uint_as_float(r.z << 16), __uint_as_float(r.z & 0xffff0000u), __uint_as_float(r.w << 16), __uint_as_float(r.w & 0xffff0000u)}; }
;                     else { b0 = *(const f32x4*)((const float*)base + o); b1 = *(const f32x4*)((const float*)base + o + 4); }
;                     const f32x4 v0 = b0 + gv[bj][0] * acc[ai][bj][m][0], v1 = b1 + gv[bj][1] * acc[ai][bj][m][1];
;                     u32x4 w; w.x = pk2(v0[0], v0[1]); w.y = pk2(v0[2], v0[3]); w.z = pk2(v1[0], v1[1]); w.w = pk2(v1[2], v1[3]);
;                     *(u32x4*)(out + o) = w; } }
	v_lshlrev_b32_e32 v102, 16, v214
	v_and_b32_e32 v103, 0xffff0000, v214
	v_lshlrev_b32_e32 v96, 16, v215
	v_and_b32_e32 v97, 0xffff0000, v215
	v_lshlrev_b32_e32 v104, 16, v216
	v_and_b32_e32 v105, 0xffff0000, v216
	v_lshlrev_b32_e32 v98, 16, v217
	v_and_b32_e32 v99, 0xffff0000, v217
	v_pk_fma_f32 v[94:95], v[94:95], v[134:135], v[96:97]
	v_pk_fma_f32 v[92:93], v[92:93], v[132:133], v[102:103]
	v_pk_fma_f32 v[96:97], v[90:91], v[130:131], v[98:99]
	v_pk_fma_f32 v[90:91], v[88:89], v[128:129], v[104:105]
	v_cvt_pk_bf16_f32 v88, v92, v93
	v_cvt_pk_bf16_f32 v89, v94, v95
	v_cvt_pk_bf16_f32 v90, v90, v91
	v_cvt_pk_bf16_f32 v91, v96, v97
	global_store_dwordx4 v[100:101], v[88:91], off
	s_mov_b64 s[98:99], 0x18000
	v_lshl_add_u64 v[246:247], v[174:175], 0, s[98:99]
	global_load_dwordx4 v[226:229], v[246:247], off offset:256
	v_or_b32_e32 v92, 48, v164
	v_ashrrev_i32_e32 v93, 31, v92
	v_lshlrev_b64 v[92:93], 10, v[92:93]
	v_lshl_add_u64 v[92:93], v[92:93], 0, v[162:163]
	v_lshlrev_b64 v[92:93], 1, v[92:93]
	v_lshl_add_u64 v[94:95], s[44:45], 0, v[92:93]
	s_waitcnt vmcnt(4)
	v_lshlrev_b32_e32 v96, 16, v218
	v_and_b32_e32 v97, 0xffff0000, v218
	v_lshlrev_b32_e32 v88, 16, v219
	v_and_b32_e32 v89, 0xffff0000, v219
	v_lshlrev_b32_e32 v98, 16, v220
	v_and_b32_e32 v99, 0xffff0000, v220
	v_lshlrev_b32_e32 v90, 16, v221
	v_and_b32_e32 v91, 0xffff0000, v221
	v_pk_fma_f32 v[86:87], v[86:87], v[126:127], v[88:89]
	v_pk_fma_f32 v[84:85], v[84:85], v[124:125], v[96:97]
	v_pk_fma_f32 v[88:89], v[82:83], v[122:123], v[90:91]
	v_pk_fma_f32 v[82:83], v[80:81], v[120:121], v[98:99]
	v_cvt_pk_bf16_f32 v80, v84, v85
	v_cvt_pk_bf16_f32 v81, v86, v87
	v_cvt_pk_bf16_f32 v82, v82, v83
	v_cvt_pk_bf16_f32 v83, v88, v89
	global_store_dwordx4 v[100:101], v[80:83], off offset:256
	v_lshl_add_u64 v[246:247], v[174:175], 0, s[16:17]
	global_load_dwordx4 v[214:217], v[246:247], off
	v_lshl_add_u64 v[84:85], s[26:27], 0, v[92:93]
	s_waitcnt vmcnt(4)
	v_lshlrev_b32_e32 v86, 16, v222
	v_and_b32_e32 v87, 0xffff0000, v222
	v_lshlrev_b32_e32 v80, 16, v223
	v_and_b32_e32 v81, 0xffff0000, v223
	v_lshlrev_b32_e32 v88, 16, v224
	v_and_b32_e32 v89, 0xffff0000, v224
	v_lshlrev_b32_e32 v82, 16, v225
	v_and_b32_e32 v83, 0xffff0000, v225
	v_pk_fma_f32 v[78:79], v[78:79], v[134:135], v[80:81]
	v_pk_fma_f32 v[76:77], v[76:77], v[132:133], v[86:87]
	v_pk_fma_f32 v[80:81], v[74:75], v[130:131], v[82:83]
	v_pk_fma_f32 v[74:75], v[72:73], v[128:129], v[88:89]
	v_cvt_pk_bf16_f32 v72, v76, v77
	v_cvt_pk_bf16_f32 v73, v78, v79
	v_cvt_pk_bf16_f32 v74, v74, v75
	v_cvt_pk_bf16_f32 v75, v80, v81
	global_store_dwordx4 v[84:85], v[72:75], off
	v_lshl_add_u64 v[246:247], v[174:175], 0, s[16:17]
	global_load_dwordx4 v[218:221], v[246:247], off offset:256
	v_lshl_add_u64 v[76:77], v[160:161], 0, s[16:17]
	v_lshl_add_u64 v[78:79], s[44:45], 0, v[76:77]
	s_waitcnt vmcnt(4)
	v_lshlrev_b32_e32 v80, 16, v226
	v_and_b32_e32 v81, 0xffff0000, v226
	v_lshlrev_b32_e32 v72, 16, v227
	v_and_b32_e32 v73, 0xffff0000, v227
	v_lshlrev_b32_e32 v82, 16, v228
	v_and_b32_e32 v83, 0xffff0000, v228
	v_lshlrev_b32_e32 v74, 16, v229
	v_and_b32_e32 v75, 0xffff0000, v229
	v_pk_fma_f32 v[70:71], v[70:71], v[126:127], v[72:73]
	v_pk_fma_f32 v[68:69], v[68:69], v[124:125], v[80:81]
	v_pk_fma_f32 v[72:73], v[66:67], v[122:123], v[74:75]
	v_pk_fma_f32 v[66:67], v[64:65], v[120:121], v[82:83]
	v_cvt_pk_bf16_f32 v64, v68, v69
	v_cvt_pk_bf16_f32 v65, v70, v71
	v_cvt_pk_bf16_f32 v66, v66, v67
	v_cvt_pk_bf16_f32 v67, v72, v73
	global_store_dwordx4 v[84:85], v[64:67], off offset:256
	v_lshl_add_u64 v[246:247], v[174:175], 0, s[18:19]
	global_load_dwordx4 v[222:225], v[246:247], off
	v_lshl_add_u64 v[68:69], s[26:27], 0, v[76:77]
	s_waitcnt vmcnt(4)
	v_lshlrev_b32_e32 v70, 16, v214
	v_and_b32_e32 v71, 0xffff0000, v214
	v_lshlrev_b32_e32 v64, 16, v215
	v_and_b32_e32 v65, 0xffff0000, v215
	v_lshlrev_b32_e32 v72, 16, v216
	v_and_b32_e32 v73, 0xffff0000, v216
	v_lshlrev_b32_e32 v66, 16, v217
	v_and_b32_e32 v67, 0xffff0000, v217
	v_pk_fma_f32 v[62:63], v[62:63], v[134:135], v[64:65]
	v_pk_fma_f32 v[60:61], v[60:61], v[132:133], v[70:71]
	v_pk_fma_f32 v[64:65], v[58:59], v[130:131], v[66:67]
	v_pk_fma_f32 v[58:59], v[56:57], v[128:129], v[72:73]
	v_cvt_pk_bf16_f32 v56, v60, v61
	v_cvt_pk_bf16_f32 v57, v62, v63
	v_cvt_pk_bf16_f32 v58, v58, v59
	v_cvt_pk_bf16_f32 v59, v64, v65
	global_store_dwordx4 v[68:69], v[56:59], off
	v_lshl_add_u64 v[246:247], v[174:175], 0, s[18:19]
	global_load_dwordx4 v[226:229], v[246:247], off offset:256
	v_lshl_add_u64 v[60:61], v[160:161], 0, s[18:19]
	v_lshl_add_u64 v[62:63], s[44:45], 0, v[60:61]
	s_waitcnt vmcnt(4)
	v_lshlrev_b32_e32 v64, 16, v218
	v_and_b32_e32 v65, 0xffff0000, v218
	v_lshlrev_b32_e32 v56, 16, v219
	v_and_b32_e32 v57, 0xffff0000, v219
	v_lshlrev_b32_e32 v66, 16, v220
	v_and_b32_e32 v67, 0xffff0000, v220
	v_lshlrev_b32_e32 v58, 16, v221
	v_and_b32_e32 v59, 0xffff0000, v221
	v_pk_fma_f32 v[54:55], v[54:55], v[126:127], v[56:57]
	v_pk_fma_f32 v[52:53], v[52:53], v[124:125], v[64:65]
	v_pk_fma_f32 v[56:57], v[50:51], v[122:123], v[58:59]
	v_pk_fma_f32 v[50:51], v[48:49], v[120:121], v[66:67]
	v_cvt_pk_bf16_f32 v48, v52, v53
	v_cvt_pk_bf16_f32 v49, v54, v55
	v_cvt_pk_bf16_f32 v50, v50, v51
	v_cvt_pk_bf16_f32 v51, v56, v57
	global_store_dwordx4 v[68:69], v[48:51], off offset:256
	v_lshl_add_u64 v[246:247], v[174:175], 0, s[20:21]
	global_load_dwordx4 v[214:217], v[246:247], off
	v_lshl_add_u64 v[52:53], s[26:27], 0, v[60:61]
	s_waitcnt vmcnt(4)
; __device__ __forceinline__ unsigned pk2(float lo, float hi) { f32x2 v = {lo, hi}; bf16x2_t b = __builtin_convertvector(v, bf16x2_t); return __builtin_bit_cast(unsigned, b); }
;     __device__ __forceinline__ void operator()(const f32x4 (&acc)[2][2][4][2], const Unit& u, int wr, int wc, int fr, int fq) const {
;     ...
;             for (int m = 0; m < 4; ++m) { const size_t off = (size_t)(row0 + ai * HALF + m * 16) * D + u.pn * BM + wc * 32 + 8 * fq;
; #pragma unroll
;                 for (int bj = 0; bj < 2; ++bj) { const size_t o = off + bj * HALF; f32x4 b0, b1;
;                     if (BASE_BF16) { const u32x4 r = *(const u32x4*)((const bf16_t*)base + o);
;                         b0 = (f32x4){__uint_as_float(r.x << 16), __uint_as_float(r.x & 0xffff0000u), __uint_as_float(r.y << 16), __uint_as_float(r.y & 0xffff0000u)};
;                         b1 = (f32x4){__uint_as_float(r.z << 16), __uint_as_float(r.z & 0xffff0000u), __uint_as_float(r.w << 16), __uint_as_float(r.w & 0xffff0000u)}; }
;                     else { b0 = *(const f32x4*)((const float*)base + o); b1 = *(const f32x4*)((const float*)base + o + 4); }
;                     const f32x4 v0 = b0 + gv[bj][0] * acc[ai][bj][m][0], v1 = b1 + gv[bj][1] * acc[ai][bj][m][1];
;                     u32x4 w; w.x = pk2(v0[0], v0[1]); w.y = pk2(v0[2], v0[3]); w.z = pk2(v1[0], v1[1]); w.w = pk2(v1[2], v1[3]);
;                     *(u32x4*)(out + o) = w; } }
	v_lshlrev_b32_e32 v54, 16, v222
	v_and_b32_e32 v55, 0xffff0000, v222
	v_lshlrev_b32_e32 v48, 16, v223
	v_and_b32_e32 v49, 0xffff0000, v223
	v_lshlrev_b32_e32 v56, 16, v224
	v_and_b32_e32 v57, 0xffff0000, v224
	v_lshlrev_b32_e32 v50, 16, v225
	v_and_b32_e32 v51, 0xffff0000, v225
	v_pk_fma_f32 v[46:47], v[46:47], v[134:135], v[48:49]
	v_pk_fma_f32 v[44:45], v[44:45], v[132:133], v[54:55]
	v_pk_fma_f32 v[48:49], v[42:43], v[130:131], v[50:51]
	v_pk_fma_f32 v[42:43], v[40:41], v[128:129], v[56:57]
	v_cvt_pk_bf16_f32 v40, v44, v45
	v_cvt_pk_bf16_f32 v41, v46, v47
	v_cvt_pk_bf16_f32 v42, v42, v43
	v_cvt_pk_bf16_f32 v43, v48, v49
	global_store_dwordx4 v[52:53], v[40:43], off
	v_lshl_add_u64 v[246:247], v[174:175], 0, s[20:21]
	global_load_dwordx4 v[218:221], v[246:247], off offset:256
	v_lshl_add_u64 v[44:45], v[160:161], 0, s[20:21]
	v_lshl_add_u64 v[46:47], s[44:45], 0, v[44:45]
	s_waitcnt vmcnt(4)
	v_lshlrev_b32_e32 v48, 16, v226
	v_and_b32_e32 v49, 0xffff0000, v226
	v_lshlrev_b32_e32 v40, 16, v227
	v_and_b32_e32 v41, 0xffff0000, v227
	v_lshlrev_b32_e32 v50, 16, v228
	v_and_b32_e32 v51, 0xffff0000, v228
	v_lshlrev_b32_e32 v42, 16, v229
	v_and_b32_e32 v43, 0xffff0000, v229
	v_pk_fma_f32 v[38:39], v[38:39], v[126:127], v[40:41]
	v_pk_fma_f32 v[36:37], v[36:37], v[124:125], v[48:49]
	v_pk_fma_f32 v[40:41], v[34:35], v[122:123], v[42:43]
	v_pk_fma_f32 v[34:35], v[32:33], v[120:121], v[50:51]
	v_cvt_pk_bf16_f32 v32, v36, v37
	v_cvt_pk_bf16_f32 v33, v38, v39
	v_cvt_pk_bf16_f32 v34, v34, v35
	v_cvt_pk_bf16_f32 v35, v40, v41
	global_store_dwordx4 v[52:53], v[32:35], off offset:256
	v_lshl_add_u64 v[246:247], v[174:175], 0, s[22:23]
	global_load_dwordx4 v[222:225], v[246:247], off
	v_lshl_add_u64 v[36:37], s[26:27], 0, v[44:45]
	s_waitcnt vmcnt(4)
	v_lshlrev_b32_e32 v38, 16, v214
	v_and_b32_e32 v39, 0xffff0000, v214
	v_lshlrev_b32_e32 v32, 16, v215
	v_and_b32_e32 v33, 0xffff0000, v215
	v_lshlrev_b32_e32 v40, 16, v216
	v_and_b32_e32 v41, 0xffff0000, v216
	v_lshlrev_b32_e32 v34, 16, v217
	v_and_b32_e32 v35, 0xffff0000, v217
	v_pk_fma_f32 v[30:31], v[30:31], v[134:135], v[32:33]
	v_pk_fma_f32 v[28:29], v[28:29], v[132:133], v[38:39]
	v_pk_fma_f32 v[32:33], v[26:27], v[130:131], v[34:35]
	v_pk_fma_f32 v[26:27], v[24:25], v[128:129], v[40:41]
	v_cvt_pk_bf16_f32 v24, v28, v29
	v_cvt_pk_bf16_f32 v25, v30, v31
	v_cvt_pk_bf16_f32 v26, v26, v27
	v_cvt_pk_bf16_f32 v27, v32, v33
	global_store_dwordx4 v[36:37], v[24:27], off
	v_lshl_add_u64 v[246:247], v[174:175], 0, s[22:23]
	global_load_dwordx4 v[226:229], v[246:247], off offset:256
	v_lshl_add_u64 v[28:29], v[160:161], 0, s[22:23]
	v_lshl_add_u64 v[30:31], s[44:45], 0, v[28:29]
	s_waitcnt vmcnt(4)
	v_lshlrev_b32_e32 v32, 16, v218
	v_and_b32_e32 v33, 0xffff0000, v218
	v_lshlrev_b32_e32 v24, 16, v219
	v_and_b32_e32 v25, 0xffff0000, v219
	v_lshlrev_b32_e32 v34, 16, v220
	v_and_b32_e32 v35, 0xffff0000, v220
	v_lshlrev_b32_e32 v26, 16, v221
	v_and_b32_e32 v27, 0xffff0000, v221
	v_pk_fma_f32 v[22:23], v[22:23], v[126:127], v[24:25]
	v_pk_fma_f32 v[20:21], v[20:21], v[124:125], v[32:33]
	v_pk_fma_f32 v[24:25], v[18:19], v[122:123], v[26:27]
	v_pk_fma_f32 v[18:19], v[16:17], v[120:121], v[34:35]
	v_cvt_pk_bf16_f32 v16, v20, v21
	v_cvt_pk_bf16_f32 v17, v22, v23
	v_cvt_pk_bf16_f32 v18, v18, v19
	v_cvt_pk_bf16_f32 v19, v24, v25
	global_store_dwordx4 v[36:37], v[16:19], off offset:256
	v_lshl_add_u64 v[20:21], s[26:27], 0, v[28:29]
	s_waitcnt vmcnt(3)
	v_lshlrev_b32_e32 v22, 16, v222
	v_and_b32_e32 v23, 0xffff0000, v222
	v_lshlrev_b32_e32 v16, 16, v223
	v_and_b32_e32 v17, 0xffff0000, v223
	v_lshlrev_b32_e32 v24, 16, v224
	v_and_b32_e32 v25, 0xffff0000, v224
	v_lshlrev_b32_e32 v18, 16, v225
	v_and_b32_e32 v19, 0xffff0000, v225
	v_pk_fma_f32 v[14:15], v[14:15], v[134:135], v[16:17]
	v_pk_fma_f32 v[12:13], v[12:13], v[132:133], v[22:23]
	v_pk_fma_f32 v[16:17], v[10:11], v[130:131], v[18:19]
	v_pk_fma_f32 v[10:11], v[8:9], v[128:129], v[24:25]
	v_cvt_pk_bf16_f32 v8, v12, v13
	v_cvt_pk_bf16_f32 v9, v14, v15
	v_cvt_pk_bf16_f32 v10, v10, v11
	v_cvt_pk_bf16_f32 v11, v16, v17
	global_store_dwordx4 v[20:21], v[8:11], off
	s_waitcnt vmcnt(2)
	v_lshlrev_b32_e32 v12, 16, v226
	v_and_b32_e32 v13, 0xffff0000, v226
	v_lshlrev_b32_e32 v8, 16, v227
	v_and_b32_e32 v9, 0xffff0000, v227
	v_lshlrev_b32_e32 v14, 16, v228
	v_and_b32_e32 v15, 0xffff0000, v228
	v_lshlrev_b32_e32 v10, 16, v229
	v_and_b32_e32 v11, 0xffff0000, v229
	v_pk_fma_f32 v[6:7], v[6:7], v[126:127], v[8:9]
	v_pk_fma_f32 v[4:5], v[4:5], v[124:125], v[12:13]
	v_pk_fma_f32 v[8:9], v[2:3], v[122:123], v[10:11]
	v_pk_fma_f32 v[2:3], v[0:1], v[120:121], v[14:15]
	v_cvt_pk_bf16_f32 v0, v4, v5
	v_cvt_pk_bf16_f32 v1, v6, v7
	v_cvt_pk_bf16_f32 v2, v2, v3
	v_cvt_pk_bf16_f32 v3, v8, v9
	global_store_dwordx4 v[20:21], v[0:3], off offset:256
	s_cbranch_vccnz .LBB0_1685
	s_andn2_b64 vcc, exec, s[10:11]
	s_cbranch_vccnz .LBB0_1684
	s_barrier
	s_branch .LBB0_1684
